# merge odd-epilogue: single vmcnt(0) before the first half replaced by per-chunk counted waits (on top of v54)
# baseline (speedup 1.0000x reference)
; DI unsigned cvtpk(float lo, float hi) { typedef float f2 __attribute__((ext_vector_type(2))); typedef __bf16 b2 __attribute__((ext_vector_type(2))); f2 v = {lo, hi}; b2 b = __builtin_convertvector(v, b2); return __builtin_bit_cast(unsigned, b); }
; DI float bflo(unsigned w) { return __uint_as_float(w << 16); }
; DI float bfhi(unsigned w) { return __uint_as_float(w & 0xffff0000u); }
;     DI void operator()(f32x4 (&acc)[2][2][4][2], const pg8::GUnit& u, int wr, int wc, int fr, int fq) const {
;     ...
;                 for (int m = 0; m < 4; ++m) { bf16_t* mp = act + (size_t)(row0 + ai * 128 + m * 16) * PITCH + C_MERGED + col0;
; #pragma unroll
;                     for (int bj = 0; bj < 2; ++bj) {
;                         const u32x4 g = gq[m][bj];
;                         const f32x4 a0 = acc[ai][bj][m][0], a1 = acc[ai][bj][m][1];
;                         float r0 = bflo(g.x) * a0[0], r1 = bfhi(g.x) * a0[1], r2 = bflo(g.y) * a0[2], r3 = bfhi(g.y) * a0[3];
;                         float r4 = bflo(g.z) * a1[0], r5 = bfhi(g.z) * a1[1], r6 = bflo(g.w) * a1[2], r7 = bfhi(g.w) * a1[3];
;                         if (z > 1) { const u32x4 pm_ = mq[m][bj];
;                             r0 += bflo(pm_.x); r1 += bfhi(pm_.x); r2 += bflo(pm_.y); r3 += bfhi(pm_.y); r4 += bflo(pm_.z); r5 += bfhi(pm_.z); r6 += bflo(pm_.w); r7 += bfhi(pm_.w); }
;                         u32x4 w; w.x = cvtpk(r0, r1); w.y = cvtpk(r2, r3); w.z = cvtpk(r4, r5); w.w = cvtpk(r6, r7);
;                         *(u32x4*)(mp + bj * 128) = w;
.Lmo_ld1_done:
	s_lshl_b32 s100, s31, 7
	s_add_u32 s22, s100, 0x1000
	s_mov_b32 s23, 0
	s_and_b64 vcc, exec, s[44:45]
	s_cbranch_vccnz .Lmo_h1nm_0
	s_waitcnt vmcnt(13)
	v_lshlrev_b32_e32 v218, 16, v190
	v_and_b32_e32 v219, 0xffff0000, v190
	v_lshlrev_b32_e32 v220, 16, v191
	v_and_b32_e32 v221, 0xffff0000, v191
	v_lshlrev_b32_e32 v222, 16, v192
	v_and_b32_e32 v223, 0xffff0000, v192
	v_lshlrev_b32_e32 v224, 16, v193
	v_and_b32_e32 v225, 0xffff0000, v193
	v_pk_mul_f32 v[218:219], v[126:127], v[218:219]
	v_pk_mul_f32 v[220:221], v[128:129], v[220:221]
	v_pk_mul_f32 v[222:223], v[122:123], v[222:223]
	v_pk_mul_f32 v[224:225], v[124:125], v[224:225]
	v_lshlrev_b32_e32 v190, 16, v158
	v_and_b32_e32 v191, 0xffff0000, v158
	v_pk_add_f32 v[218:219], v[218:219], v[190:191]
	v_lshlrev_b32_e32 v192, 16, v159
	v_and_b32_e32 v193, 0xffff0000, v159
	v_pk_add_f32 v[220:221], v[220:221], v[192:193]
	v_lshlrev_b32_e32 v190, 16, v160
	v_and_b32_e32 v191, 0xffff0000, v160
	v_pk_add_f32 v[222:223], v[222:223], v[190:191]
	v_lshlrev_b32_e32 v192, 16, v161
	v_and_b32_e32 v193, 0xffff0000, v161
	v_pk_add_f32 v[224:225], v[224:225], v[192:193]
	v_cvt_pk_bf16_f32 v218, v218, v219
	v_cvt_pk_bf16_f32 v219, v220, v221
	v_cvt_pk_bf16_f32 v220, v222, v223
	v_cvt_pk_bf16_f32 v221, v224, v225
	global_store_dwordx4 v[252:253], v[218:221], off offset:1024
	v_lshl_add_u64 v[190:191], v[252:253], 0, s[22:23]
	v_lshl_add_u64 v[158:159], v[252:253], 0, s[100:101]
	global_load_dwordx4 v[190:193], v[190:191], off offset:1024
	global_load_dwordx4 v[158:161], v[158:159], off offset:1024
	s_branch .Lmo_h1e_0
.Lmo_h1nm_0:
	s_waitcnt vmcnt(7)
	v_lshlrev_b32_e32 v218, 16, v190
	v_and_b32_e32 v219, 0xffff0000, v190
	v_lshlrev_b32_e32 v220, 16, v191
	v_and_b32_e32 v221, 0xffff0000, v191
	v_lshlrev_b32_e32 v222, 16, v192
	v_and_b32_e32 v223, 0xffff0000, v192
	v_lshlrev_b32_e32 v224, 16, v193
	v_and_b32_e32 v225, 0xffff0000, v193
	v_pk_mul_f32 v[218:219], v[126:127], v[218:219]
	v_pk_mul_f32 v[220:221], v[128:129], v[220:221]
	v_pk_mul_f32 v[222:223], v[122:123], v[222:223]
	v_pk_mul_f32 v[224:225], v[124:125], v[224:225]
	v_cvt_pk_bf16_f32 v218, v218, v219
	v_cvt_pk_bf16_f32 v219, v220, v221
	v_cvt_pk_bf16_f32 v220, v222, v223
	v_cvt_pk_bf16_f32 v221, v224, v225
	global_store_dwordx4 v[252:253], v[218:221], off offset:1024
	v_lshl_add_u64 v[190:191], v[252:253], 0, s[22:23]
	s_nop 0
	global_load_dwordx4 v[190:193], v[190:191], off offset:1024
.Lmo_h1e_0:
	s_and_b64 vcc, exec, s[44:45]
	s_cbranch_vccnz .Lmo_h1nm_1
	s_waitcnt vmcnt(15)
	v_lshlrev_b32_e32 v218, 16, v186
	v_and_b32_e32 v219, 0xffff0000, v186
	v_lshlrev_b32_e32 v220, 16, v187
	v_and_b32_e32 v221, 0xffff0000, v187
	v_lshlrev_b32_e32 v222, 16, v188
	v_and_b32_e32 v223, 0xffff0000, v188
	v_lshlrev_b32_e32 v224, 16, v189
	v_and_b32_e32 v225, 0xffff0000, v189
	v_pk_mul_f32 v[218:219], v[118:119], v[218:219]
	v_pk_mul_f32 v[220:221], v[120:121], v[220:221]
	v_pk_mul_f32 v[222:223], v[114:115], v[222:223]
	v_pk_mul_f32 v[224:225], v[116:117], v[224:225]
	v_lshlrev_b32_e32 v186, 16, v154
	v_and_b32_e32 v187, 0xffff0000, v154
	v_pk_add_f32 v[218:219], v[218:219], v[186:187]
	v_lshlrev_b32_e32 v188, 16, v155
	v_and_b32_e32 v189, 0xffff0000, v155
	v_pk_add_f32 v[220:221], v[220:221], v[188:189]
	v_lshlrev_b32_e32 v186, 16, v156
	v_and_b32_e32 v187, 0xffff0000, v156
	v_pk_add_f32 v[222:223], v[222:223], v[186:187]
	v_lshlrev_b32_e32 v188, 16, v157
	v_and_b32_e32 v189, 0xffff0000, v157
	v_pk_add_f32 v[224:225], v[224:225], v[188:189]
	v_cvt_pk_bf16_f32 v218, v218, v219
	v_cvt_pk_bf16_f32 v219, v220, v221
	v_cvt_pk_bf16_f32 v220, v222, v223
	v_cvt_pk_bf16_f32 v221, v224, v225
	global_store_dwordx4 v[252:253], v[218:221], off offset:1280
	v_lshl_add_u64 v[186:187], v[252:253], 0, s[22:23]
	v_lshl_add_u64 v[154:155], v[252:253], 0, s[100:101]
	global_load_dwordx4 v[186:189], v[186:187], off offset:1280
	global_load_dwordx4 v[154:157], v[154:155], off offset:1280
	s_branch .Lmo_h1e_1
.Lmo_h1nm_1:
	s_waitcnt vmcnt(8)
	v_lshlrev_b32_e32 v218, 16, v186
	v_and_b32_e32 v219, 0xffff0000, v186
	v_lshlrev_b32_e32 v220, 16, v187
	v_and_b32_e32 v221, 0xffff0000, v187
	v_lshlrev_b32_e32 v222, 16, v188
	v_and_b32_e32 v223, 0xffff0000, v188
	v_lshlrev_b32_e32 v224, 16, v189
	v_and_b32_e32 v225, 0xffff0000, v189
	v_pk_mul_f32 v[218:219], v[118:119], v[218:219]
	v_pk_mul_f32 v[220:221], v[120:121], v[220:221]
	v_pk_mul_f32 v[222:223], v[114:115], v[222:223]
	v_pk_mul_f32 v[224:225], v[116:117], v[224:225]
	v_cvt_pk_bf16_f32 v218, v218, v219
	v_cvt_pk_bf16_f32 v219, v220, v221
	v_cvt_pk_bf16_f32 v220, v222, v223
	v_cvt_pk_bf16_f32 v221, v224, v225
	global_store_dwordx4 v[252:253], v[218:221], off offset:1280
	v_lshl_add_u64 v[186:187], v[252:253], 0, s[22:23]
	s_nop 0
	global_load_dwordx4 v[186:189], v[186:187], off offset:1280
.Lmo_h1e_1:
	v_lshl_add_u64 v[252:253], v[252:253], 0, s[98:99]
	s_and_b64 vcc, exec, s[44:45]
	s_cbranch_vccnz .Lmo_h1nm_2
	s_waitcnt vmcnt(15)
	v_lshlrev_b32_e32 v218, 16, v182
	v_and_b32_e32 v219, 0xffff0000, v182
	v_lshlrev_b32_e32 v220, 16, v183
	v_and_b32_e32 v221, 0xffff0000, v183
	v_lshlrev_b32_e32 v222, 16, v184
	v_and_b32_e32 v223, 0xffff0000, v184
	v_lshlrev_b32_e32 v224, 16, v185
	v_and_b32_e32 v225, 0xffff0000, v185
	v_pk_mul_f32 v[218:219], v[110:111], v[218:219]
	v_pk_mul_f32 v[220:221], v[112:113], v[220:221]
	v_pk_mul_f32 v[222:223], v[106:107], v[222:223]
	v_pk_mul_f32 v[224:225], v[108:109], v[224:225]
	v_lshlrev_b32_e32 v182, 16, v150
	v_and_b32_e32 v183, 0xffff0000, v150
	v_pk_add_f32 v[218:219], v[218:219], v[182:183]
	v_lshlrev_b32_e32 v184, 16, v151
	v_and_b32_e32 v185, 0xffff0000, v151
	v_pk_add_f32 v[220:221], v[220:221], v[184:185]
	v_lshlrev_b32_e32 v182, 16, v152
	v_and_b32_e32 v183, 0xffff0000, v152
	v_pk_add_f32 v[222:223], v[222:223], v[182:183]
	v_lshlrev_b32_e32 v184, 16, v153
	v_and_b32_e32 v185, 0xffff0000, v153
	v_pk_add_f32 v[224:225], v[224:225], v[184:185]
	v_cvt_pk_bf16_f32 v218, v218, v219
	v_cvt_pk_bf16_f32 v219, v220, v221
	v_cvt_pk_bf16_f32 v220, v222, v223
	v_cvt_pk_bf16_f32 v221, v224, v225
	global_store_dwordx4 v[252:253], v[218:221], off offset:1024
	v_lshl_add_u64 v[182:183], v[252:253], 0, s[22:23]
	v_lshl_add_u64 v[150:151], v[252:253], 0, s[100:101]
	global_load_dwordx4 v[182:185], v[182:183], off offset:1024
	global_load_dwordx4 v[150:153], v[150:151], off offset:1024
	s_branch .Lmo_h1e_2
; DI unsigned cvtpk(float lo, float hi) { typedef float f2 __attribute__((ext_vector_type(2))); typedef __bf16 b2 __attribute__((ext_vector_type(2))); f2 v = {lo, hi}; b2 b = __builtin_convertvector(v, b2); return __builtin_bit_cast(unsigned, b); }
; DI float bflo(unsigned w) { return __uint_as_float(w << 16); }
; DI float bfhi(unsigned w) { return __uint_as_float(w & 0xffff0000u); }
;     DI void operator()(f32x4 (&acc)[2][2][4][2], const pg8::GUnit& u, int wr, int wc, int fr, int fq) const {
;     ...
;                 for (int m = 0; m < 4; ++m) { bf16_t* mp = act + (size_t)(row0 + ai * 128 + m * 16) * PITCH + C_MERGED + col0;
; #pragma unroll
;                     for (int bj = 0; bj < 2; ++bj) {
;                         const u32x4 g = gq[m][bj];
;                         const f32x4 a0 = acc[ai][bj][m][0], a1 = acc[ai][bj][m][1];
;                         float r0 = bflo(g.x) * a0[0], r1 = bfhi(g.x) * a0[1], r2 = bflo(g.y) * a0[2], r3 = bfhi(g.y) * a0[3];
;                         float r4 = bflo(g.z) * a1[0], r5 = bfhi(g.z) * a1[1], r6 = bflo(g.w) * a1[2], r7 = bfhi(g.w) * a1[3];
;                         if (z > 1) { const u32x4 pm_ = mq[m][bj];
;                             r0 += bflo(pm_.x); r1 += bfhi(pm_.x); r2 += bflo(pm_.y); r3 += bfhi(pm_.y); r4 += bflo(pm_.z); r5 += bfhi(pm_.z); r6 += bflo(pm_.w); r7 += bfhi(pm_.w); }
;                         u32x4 w; w.x = cvtpk(r0, r1); w.y = cvtpk(r2, r3); w.z = cvtpk(r4, r5); w.w = cvtpk(r6, r7);
;                         *(u32x4*)(mp + bj * 128) = w;
.Lmo_h1nm_2:
	s_waitcnt vmcnt(9)
	v_lshlrev_b32_e32 v218, 16, v182
	v_and_b32_e32 v219, 0xffff0000, v182
	v_lshlrev_b32_e32 v220, 16, v183
	v_and_b32_e32 v221, 0xffff0000, v183
	v_lshlrev_b32_e32 v222, 16, v184
	v_and_b32_e32 v223, 0xffff0000, v184
	v_lshlrev_b32_e32 v224, 16, v185
	v_and_b32_e32 v225, 0xffff0000, v185
	v_pk_mul_f32 v[218:219], v[110:111], v[218:219]
	v_pk_mul_f32 v[220:221], v[112:113], v[220:221]
	v_pk_mul_f32 v[222:223], v[106:107], v[222:223]
	v_pk_mul_f32 v[224:225], v[108:109], v[224:225]
	v_cvt_pk_bf16_f32 v218, v218, v219
	v_cvt_pk_bf16_f32 v219, v220, v221
	v_cvt_pk_bf16_f32 v220, v222, v223
	v_cvt_pk_bf16_f32 v221, v224, v225
	global_store_dwordx4 v[252:253], v[218:221], off offset:1024
	v_lshl_add_u64 v[182:183], v[252:253], 0, s[22:23]
	s_nop 0
	global_load_dwordx4 v[182:185], v[182:183], off offset:1024
.Lmo_h1e_2:
	s_and_b64 vcc, exec, s[44:45]
	s_cbranch_vccnz .Lmo_h1nm_3
	s_waitcnt vmcnt(17)
	v_lshlrev_b32_e32 v218, 16, v178
	v_and_b32_e32 v219, 0xffff0000, v178
	v_lshlrev_b32_e32 v220, 16, v179
	v_and_b32_e32 v221, 0xffff0000, v179
	v_lshlrev_b32_e32 v222, 16, v180
	v_and_b32_e32 v223, 0xffff0000, v180
	v_lshlrev_b32_e32 v224, 16, v181
	v_and_b32_e32 v225, 0xffff0000, v181
	v_pk_mul_f32 v[218:219], v[102:103], v[218:219]
	v_pk_mul_f32 v[220:221], v[104:105], v[220:221]
	v_pk_mul_f32 v[222:223], v[98:99], v[222:223]
	v_pk_mul_f32 v[224:225], v[100:101], v[224:225]
	v_lshlrev_b32_e32 v178, 16, v146
	v_and_b32_e32 v179, 0xffff0000, v146
	v_pk_add_f32 v[218:219], v[218:219], v[178:179]
	v_lshlrev_b32_e32 v180, 16, v147
	v_and_b32_e32 v181, 0xffff0000, v147
	v_pk_add_f32 v[220:221], v[220:221], v[180:181]
	v_lshlrev_b32_e32 v178, 16, v148
	v_and_b32_e32 v179, 0xffff0000, v148
	v_pk_add_f32 v[222:223], v[222:223], v[178:179]
	v_lshlrev_b32_e32 v180, 16, v149
	v_and_b32_e32 v181, 0xffff0000, v149
	v_pk_add_f32 v[224:225], v[224:225], v[180:181]
	v_cvt_pk_bf16_f32 v218, v218, v219
	v_cvt_pk_bf16_f32 v219, v220, v221
	v_cvt_pk_bf16_f32 v220, v222, v223
	v_cvt_pk_bf16_f32 v221, v224, v225
	global_store_dwordx4 v[252:253], v[218:221], off offset:1280
	v_lshl_add_u64 v[178:179], v[252:253], 0, s[22:23]
	v_lshl_add_u64 v[146:147], v[252:253], 0, s[100:101]
	global_load_dwordx4 v[178:181], v[178:179], off offset:1280
	global_load_dwordx4 v[146:149], v[146:147], off offset:1280
	s_branch .Lmo_h1e_3
.Lmo_h1nm_3:
	s_waitcnt vmcnt(10)
	v_lshlrev_b32_e32 v218, 16, v178
	v_and_b32_e32 v219, 0xffff0000, v178
	v_lshlrev_b32_e32 v220, 16, v179
	v_and_b32_e32 v221, 0xffff0000, v179
	v_lshlrev_b32_e32 v222, 16, v180
	v_and_b32_e32 v223, 0xffff0000, v180
	v_lshlrev_b32_e32 v224, 16, v181
	v_and_b32_e32 v225, 0xffff0000, v181
	v_pk_mul_f32 v[218:219], v[102:103], v[218:219]
	v_pk_mul_f32 v[220:221], v[104:105], v[220:221]
	v_pk_mul_f32 v[222:223], v[98:99], v[222:223]
	v_pk_mul_f32 v[224:225], v[100:101], v[224:225]
	v_cvt_pk_bf16_f32 v218, v218, v219
	v_cvt_pk_bf16_f32 v219, v220, v221
	v_cvt_pk_bf16_f32 v220, v222, v223
	v_cvt_pk_bf16_f32 v221, v224, v225
	global_store_dwordx4 v[252:253], v[218:221], off offset:1280
	v_lshl_add_u64 v[178:179], v[252:253], 0, s[22:23]
	s_nop 0
	global_load_dwordx4 v[178:181], v[178:179], off offset:1280
.Lmo_h1e_3:
	v_lshl_add_u64 v[252:253], v[252:253], 0, s[98:99]
	s_and_b64 vcc, exec, s[44:45]
	s_cbranch_vccnz .Lmo_h1nm_4
	s_waitcnt vmcnt(17)
	v_lshlrev_b32_e32 v218, 16, v174
	v_and_b32_e32 v219, 0xffff0000, v174
	v_lshlrev_b32_e32 v220, 16, v175
	v_and_b32_e32 v221, 0xffff0000, v175
	v_lshlrev_b32_e32 v222, 16, v176
	v_and_b32_e32 v223, 0xffff0000, v176
	v_lshlrev_b32_e32 v224, 16, v177
	v_and_b32_e32 v225, 0xffff0000, v177
	v_pk_mul_f32 v[218:219], v[94:95], v[218:219]
	v_pk_mul_f32 v[220:221], v[96:97], v[220:221]
	v_pk_mul_f32 v[222:223], v[90:91], v[222:223]
	v_pk_mul_f32 v[224:225], v[92:93], v[224:225]
	v_lshlrev_b32_e32 v174, 16, v142
	v_and_b32_e32 v175, 0xffff0000, v142
	v_pk_add_f32 v[218:219], v[218:219], v[174:175]
	v_lshlrev_b32_e32 v176, 16, v143
	v_and_b32_e32 v177, 0xffff0000, v143
	v_pk_add_f32 v[220:221], v[220:221], v[176:177]
	v_lshlrev_b32_e32 v174, 16, v144
	v_and_b32_e32 v175, 0xffff0000, v144
	v_pk_add_f32 v[222:223], v[222:223], v[174:175]
	v_lshlrev_b32_e32 v176, 16, v145
	v_and_b32_e32 v177, 0xffff0000, v145
	v_pk_add_f32 v[224:225], v[224:225], v[176:177]
	v_cvt_pk_bf16_f32 v218, v218, v219
	v_cvt_pk_bf16_f32 v219, v220, v221
	v_cvt_pk_bf16_f32 v220, v222, v223
	v_cvt_pk_bf16_f32 v221, v224, v225
	global_store_dwordx4 v[252:253], v[218:221], off offset:1024
	v_lshl_add_u64 v[174:175], v[252:253], 0, s[22:23]
	v_lshl_add_u64 v[142:143], v[252:253], 0, s[100:101]
	global_load_dwordx4 v[174:177], v[174:175], off offset:1024
	global_load_dwordx4 v[142:145], v[142:143], off offset:1024
	s_branch .Lmo_h1e_4
.Lmo_h1nm_4:
	s_waitcnt vmcnt(11)
	v_lshlrev_b32_e32 v218, 16, v174
	v_and_b32_e32 v219, 0xffff0000, v174
	v_lshlrev_b32_e32 v220, 16, v175
	v_and_b32_e32 v221, 0xffff0000, v175
	v_lshlrev_b32_e32 v222, 16, v176
	v_and_b32_e32 v223, 0xffff0000, v176
	v_lshlrev_b32_e32 v224, 16, v177
	v_and_b32_e32 v225, 0xffff0000, v177
	v_pk_mul_f32 v[218:219], v[94:95], v[218:219]
	v_pk_mul_f32 v[220:221], v[96:97], v[220:221]
	v_pk_mul_f32 v[222:223], v[90:91], v[222:223]
	v_pk_mul_f32 v[224:225], v[92:93], v[224:225]
	v_cvt_pk_bf16_f32 v218, v218, v219
	v_cvt_pk_bf16_f32 v219, v220, v221
	v_cvt_pk_bf16_f32 v220, v222, v223
	v_cvt_pk_bf16_f32 v221, v224, v225
	global_store_dwordx4 v[252:253], v[218:221], off offset:1024
	v_lshl_add_u64 v[174:175], v[252:253], 0, s[22:23]
	s_nop 0
	global_load_dwordx4 v[174:177], v[174:175], off offset:1024
; DI unsigned cvtpk(float lo, float hi) { typedef float f2 __attribute__((ext_vector_type(2))); typedef __bf16 b2 __attribute__((ext_vector_type(2))); f2 v = {lo, hi}; b2 b = __builtin_convertvector(v, b2); return __builtin_bit_cast(unsigned, b); }
; DI float bflo(unsigned w) { return __uint_as_float(w << 16); }
; DI float bfhi(unsigned w) { return __uint_as_float(w & 0xffff0000u); }
;     DI void operator()(f32x4 (&acc)[2][2][4][2], const pg8::GUnit& u, int wr, int wc, int fr, int fq) const {
;     ...
;                 for (int m = 0; m < 4; ++m) { bf16_t* mp = act + (size_t)(row0 + ai * 128 + m * 16) * PITCH + C_MERGED + col0;
; #pragma unroll
;                     for (int bj = 0; bj < 2; ++bj) {
;                         const u32x4 g = gq[m][bj];
;                         const f32x4 a0 = acc[ai][bj][m][0], a1 = acc[ai][bj][m][1];
;                         float r0 = bflo(g.x) * a0[0], r1 = bfhi(g.x) * a0[1], r2 = bflo(g.y) * a0[2], r3 = bfhi(g.y) * a0[3];
;                         float r4 = bflo(g.z) * a1[0], r5 = bfhi(g.z) * a1[1], r6 = bflo(g.w) * a1[2], r7 = bfhi(g.w) * a1[3];
;                         if (z > 1) { const u32x4 pm_ = mq[m][bj];
;                             r0 += bflo(pm_.x); r1 += bfhi(pm_.x); r2 += bflo(pm_.y); r3 += bfhi(pm_.y); r4 += bflo(pm_.z); r5 += bfhi(pm_.z); r6 += bflo(pm_.w); r7 += bfhi(pm_.w); }
;                         u32x4 w; w.x = cvtpk(r0, r1); w.y = cvtpk(r2, r3); w.z = cvtpk(r4, r5); w.w = cvtpk(r6, r7);
;                         *(u32x4*)(mp + bj * 128) = w;
.Lmo_h1e_4:
	s_and_b64 vcc, exec, s[44:45]
	s_cbranch_vccnz .Lmo_h1nm_5
	s_waitcnt vmcnt(19)
	v_lshlrev_b32_e32 v218, 16, v170
	v_and_b32_e32 v219, 0xffff0000, v170
	v_lshlrev_b32_e32 v220, 16, v171
	v_and_b32_e32 v221, 0xffff0000, v171
	v_lshlrev_b32_e32 v222, 16, v172
	v_and_b32_e32 v223, 0xffff0000, v172
	v_lshlrev_b32_e32 v224, 16, v173
	v_and_b32_e32 v225, 0xffff0000, v173
	v_pk_mul_f32 v[218:219], v[86:87], v[218:219]
	v_pk_mul_f32 v[220:221], v[88:89], v[220:221]
	v_pk_mul_f32 v[222:223], v[82:83], v[222:223]
	v_pk_mul_f32 v[224:225], v[84:85], v[224:225]
	v_lshlrev_b32_e32 v170, 16, v138
	v_and_b32_e32 v171, 0xffff0000, v138
	v_pk_add_f32 v[218:219], v[218:219], v[170:171]
	v_lshlrev_b32_e32 v172, 16, v139
	v_and_b32_e32 v173, 0xffff0000, v139
	v_pk_add_f32 v[220:221], v[220:221], v[172:173]
	v_lshlrev_b32_e32 v170, 16, v140
	v_and_b32_e32 v171, 0xffff0000, v140
	v_pk_add_f32 v[222:223], v[222:223], v[170:171]
	v_lshlrev_b32_e32 v172, 16, v141
	v_and_b32_e32 v173, 0xffff0000, v141
	v_pk_add_f32 v[224:225], v[224:225], v[172:173]
	v_cvt_pk_bf16_f32 v218, v218, v219
	v_cvt_pk_bf16_f32 v219, v220, v221
	v_cvt_pk_bf16_f32 v220, v222, v223
	v_cvt_pk_bf16_f32 v221, v224, v225
	global_store_dwordx4 v[252:253], v[218:221], off offset:1280
	v_lshl_add_u64 v[170:171], v[252:253], 0, s[22:23]
	v_lshl_add_u64 v[138:139], v[252:253], 0, s[100:101]
	global_load_dwordx4 v[170:173], v[170:171], off offset:1280
	global_load_dwordx4 v[138:141], v[138:139], off offset:1280
	s_branch .Lmo_h1e_5
.Lmo_h1nm_5:
	s_waitcnt vmcnt(12)
	v_lshlrev_b32_e32 v218, 16, v170
	v_and_b32_e32 v219, 0xffff0000, v170
	v_lshlrev_b32_e32 v220, 16, v171
	v_and_b32_e32 v221, 0xffff0000, v171
	v_lshlrev_b32_e32 v222, 16, v172
	v_and_b32_e32 v223, 0xffff0000, v172
	v_lshlrev_b32_e32 v224, 16, v173
	v_and_b32_e32 v225, 0xffff0000, v173
	v_pk_mul_f32 v[218:219], v[86:87], v[218:219]
	v_pk_mul_f32 v[220:221], v[88:89], v[220:221]
	v_pk_mul_f32 v[222:223], v[82:83], v[222:223]
	v_pk_mul_f32 v[224:225], v[84:85], v[224:225]
	v_cvt_pk_bf16_f32 v218, v218, v219
	v_cvt_pk_bf16_f32 v219, v220, v221
	v_cvt_pk_bf16_f32 v220, v222, v223
	v_cvt_pk_bf16_f32 v221, v224, v225
	global_store_dwordx4 v[252:253], v[218:221], off offset:1280
	v_lshl_add_u64 v[170:171], v[252:253], 0, s[22:23]
	s_nop 0
	global_load_dwordx4 v[170:173], v[170:171], off offset:1280
.Lmo_h1e_5:
	v_lshl_add_u64 v[252:253], v[252:253], 0, s[98:99]
	s_and_b64 vcc, exec, s[44:45]
	s_cbranch_vccnz .Lmo_h1nm_6
	s_waitcnt vmcnt(19)
	v_lshlrev_b32_e32 v218, 16, v166
	v_and_b32_e32 v219, 0xffff0000, v166
	v_lshlrev_b32_e32 v220, 16, v167
	v_and_b32_e32 v221, 0xffff0000, v167
	v_lshlrev_b32_e32 v222, 16, v168
	v_and_b32_e32 v223, 0xffff0000, v168
	v_lshlrev_b32_e32 v224, 16, v169
	v_and_b32_e32 v225, 0xffff0000, v169
	v_pk_mul_f32 v[218:219], v[78:79], v[218:219]
	v_pk_mul_f32 v[220:221], v[80:81], v[220:221]
	v_pk_mul_f32 v[222:223], v[74:75], v[222:223]
	v_pk_mul_f32 v[224:225], v[76:77], v[224:225]
	v_lshlrev_b32_e32 v166, 16, v134
	v_and_b32_e32 v167, 0xffff0000, v134
	v_pk_add_f32 v[218:219], v[218:219], v[166:167]
	v_lshlrev_b32_e32 v168, 16, v135
	v_and_b32_e32 v169, 0xffff0000, v135
	v_pk_add_f32 v[220:221], v[220:221], v[168:169]
	v_lshlrev_b32_e32 v166, 16, v136
	v_and_b32_e32 v167, 0xffff0000, v136
	v_pk_add_f32 v[222:223], v[222:223], v[166:167]
	v_lshlrev_b32_e32 v168, 16, v137
	v_and_b32_e32 v169, 0xffff0000, v137
	v_pk_add_f32 v[224:225], v[224:225], v[168:169]
	v_cvt_pk_bf16_f32 v218, v218, v219
	v_cvt_pk_bf16_f32 v219, v220, v221
	v_cvt_pk_bf16_f32 v220, v222, v223
	v_cvt_pk_bf16_f32 v221, v224, v225
	global_store_dwordx4 v[252:253], v[218:221], off offset:1024
	v_lshl_add_u64 v[166:167], v[252:253], 0, s[22:23]
	v_lshl_add_u64 v[134:135], v[252:253], 0, s[100:101]
	global_load_dwordx4 v[166:169], v[166:167], off offset:1024
	global_load_dwordx4 v[134:137], v[134:135], off offset:1024
	s_branch .Lmo_h1e_6
; DI unsigned cvtpk(float lo, float hi) { typedef float f2 __attribute__((ext_vector_type(2))); typedef __bf16 b2 __attribute__((ext_vector_type(2))); f2 v = {lo, hi}; b2 b = __builtin_convertvector(v, b2); return __builtin_bit_cast(unsigned, b); }
; DI float bflo(unsigned w) { return __uint_as_float(w << 16); }
; DI float bfhi(unsigned w) { return __uint_as_float(w & 0xffff0000u); }
;     DI void operator()(f32x4 (&acc)[2][2][4][2], const pg8::GUnit& u, int wr, int wc, int fr, int fq) const {
;     ...
;                 for (int m = 0; m < 4; ++m) { bf16_t* mp = act + (size_t)(row0 + ai * 128 + m * 16) * PITCH + C_MERGED + col0;
; #pragma unroll
;                     for (int bj = 0; bj < 2; ++bj) {
;                         const u32x4 g = gq[m][bj];
;                         const f32x4 a0 = acc[ai][bj][m][0], a1 = acc[ai][bj][m][1];
;                         float r0 = bflo(g.x) * a0[0], r1 = bfhi(g.x) * a0[1], r2 = bflo(g.y) * a0[2], r3 = bfhi(g.y) * a0[3];
;                         float r4 = bflo(g.z) * a1[0], r5 = bfhi(g.z) * a1[1], r6 = bflo(g.w) * a1[2], r7 = bfhi(g.w) * a1[3];
;                         if (z > 1) { const u32x4 pm_ = mq[m][bj];
;                             r0 += bflo(pm_.x); r1 += bfhi(pm_.x); r2 += bflo(pm_.y); r3 += bfhi(pm_.y); r4 += bflo(pm_.z); r5 += bfhi(pm_.z); r6 += bflo(pm_.w); r7 += bfhi(pm_.w); }
;                         u32x4 w; w.x = cvtpk(r0, r1); w.y = cvtpk(r2, r3); w.z = cvtpk(r4, r5); w.w = cvtpk(r6, r7);
;                         *(u32x4*)(mp + bj * 128) = w;
.Lmo_h1nm_6:
	s_waitcnt vmcnt(13)
	v_lshlrev_b32_e32 v218, 16, v166
	v_and_b32_e32 v219, 0xffff0000, v166
	v_lshlrev_b32_e32 v220, 16, v167
	v_and_b32_e32 v221, 0xffff0000, v167
	v_lshlrev_b32_e32 v222, 16, v168
	v_and_b32_e32 v223, 0xffff0000, v168
	v_lshlrev_b32_e32 v224, 16, v169
	v_and_b32_e32 v225, 0xffff0000, v169
	v_pk_mul_f32 v[218:219], v[78:79], v[218:219]
	v_pk_mul_f32 v[220:221], v[80:81], v[220:221]
	v_pk_mul_f32 v[222:223], v[74:75], v[222:223]
	v_pk_mul_f32 v[224:225], v[76:77], v[224:225]
	v_cvt_pk_bf16_f32 v218, v218, v219
	v_cvt_pk_bf16_f32 v219, v220, v221
	v_cvt_pk_bf16_f32 v220, v222, v223
	v_cvt_pk_bf16_f32 v221, v224, v225
	global_store_dwordx4 v[252:253], v[218:221], off offset:1024
	v_lshl_add_u64 v[166:167], v[252:253], 0, s[22:23]
	s_nop 0
	global_load_dwordx4 v[166:169], v[166:167], off offset:1024
.Lmo_h1e_6:
	s_and_b64 vcc, exec, s[44:45]
	s_cbranch_vccnz .Lmo_h1nm_7
	s_waitcnt vmcnt(21)
	v_lshlrev_b32_e32 v218, 16, v162
	v_and_b32_e32 v219, 0xffff0000, v162
	v_lshlrev_b32_e32 v220, 16, v163
	v_and_b32_e32 v221, 0xffff0000, v163
	v_lshlrev_b32_e32 v222, 16, v164
	v_and_b32_e32 v223, 0xffff0000, v164
	v_lshlrev_b32_e32 v224, 16, v165
	v_and_b32_e32 v225, 0xffff0000, v165
	v_pk_mul_f32 v[218:219], v[70:71], v[218:219]
	v_pk_mul_f32 v[220:221], v[72:73], v[220:221]
	v_pk_mul_f32 v[222:223], v[66:67], v[222:223]
	v_pk_mul_f32 v[224:225], v[68:69], v[224:225]
	v_lshlrev_b32_e32 v162, 16, v130
	v_and_b32_e32 v163, 0xffff0000, v130
	v_pk_add_f32 v[218:219], v[218:219], v[162:163]
	v_lshlrev_b32_e32 v164, 16, v131
	v_and_b32_e32 v165, 0xffff0000, v131
	v_pk_add_f32 v[220:221], v[220:221], v[164:165]
	v_lshlrev_b32_e32 v162, 16, v132
	v_and_b32_e32 v163, 0xffff0000, v132
	v_pk_add_f32 v[222:223], v[222:223], v[162:163]
	v_lshlrev_b32_e32 v164, 16, v133
	v_and_b32_e32 v165, 0xffff0000, v133
	v_pk_add_f32 v[224:225], v[224:225], v[164:165]
	v_cvt_pk_bf16_f32 v218, v218, v219
	v_cvt_pk_bf16_f32 v219, v220, v221
	v_cvt_pk_bf16_f32 v220, v222, v223
	v_cvt_pk_bf16_f32 v221, v224, v225
	global_store_dwordx4 v[252:253], v[218:221], off offset:1280
	v_lshl_add_u64 v[162:163], v[252:253], 0, s[22:23]
	v_lshl_add_u64 v[130:131], v[252:253], 0, s[100:101]
	global_load_dwordx4 v[162:165], v[162:163], off offset:1280
	global_load_dwordx4 v[130:133], v[130:131], off offset:1280
	s_branch .Lmo_h1e_7
.Lmo_h1nm_7:
	s_waitcnt vmcnt(14)
	v_lshlrev_b32_e32 v218, 16, v162
	v_and_b32_e32 v219, 0xffff0000, v162
	v_lshlrev_b32_e32 v220, 16, v163
	v_and_b32_e32 v221, 0xffff0000, v163
	v_lshlrev_b32_e32 v222, 16, v164
	v_and_b32_e32 v223, 0xffff0000, v164
	v_lshlrev_b32_e32 v224, 16, v165
	v_and_b32_e32 v225, 0xffff0000, v165
	v_pk_mul_f32 v[218:219], v[70:71], v[218:219]
	v_pk_mul_f32 v[220:221], v[72:73], v[220:221]
	v_pk_mul_f32 v[222:223], v[66:67], v[222:223]
	v_pk_mul_f32 v[224:225], v[68:69], v[224:225]
	v_cvt_pk_bf16_f32 v218, v218, v219
	v_cvt_pk_bf16_f32 v219, v220, v221
	v_cvt_pk_bf16_f32 v220, v222, v223
	v_cvt_pk_bf16_f32 v221, v224, v225
	global_store_dwordx4 v[252:253], v[218:221], off offset:1280
	v_lshl_add_u64 v[162:163], v[252:253], 0, s[22:23]
	s_nop 0
	global_load_dwordx4 v[162:165], v[162:163], off offset:1280
